# stack11 plus: XCD leader leaves the barrier without waiting for the acks of its release atomics
# baseline (speedup 1.0000x reference)
.LBB0_113:
	s_or_b64 exec, exec, s[10:11]
.LBB0_114:
	s_or_b64 exec, exec, s[4:5]
	s_waitcnt lgkmcnt(0)
	s_barrier

.LBB0_207:
	s_or_b64 exec, exec, s[10:11]
.LBB0_208:
	s_or_b64 exec, exec, s[4:5]
	s_waitcnt lgkmcnt(0)
	s_barrier

.LBB0_304:
	s_or_b64 exec, exec, s[10:11]
.LBB0_305:
	s_or_b64 exec, exec, s[4:5]
	s_waitcnt lgkmcnt(0)
	s_barrier

.LBB0_376:
	s_or_b64 exec, exec, s[10:11]
.LBB0_377:
	s_or_b64 exec, exec, s[4:5]
	s_waitcnt lgkmcnt(0)
	s_barrier

.LBB0_475:
	s_or_b64 exec, exec, s[10:11]
.LBB0_476:
	s_or_b64 exec, exec, s[4:5]
	s_waitcnt lgkmcnt(0)
	s_barrier

.LBB0_552:
	s_or_b64 exec, exec, s[10:11]
.LBB0_553:
	s_or_b64 exec, exec, s[4:5]
	s_waitcnt lgkmcnt(0)
	s_barrier

.LBB0_633:
	s_or_b64 exec, exec, s[10:11]
.LBB0_634:
	s_or_b64 exec, exec, s[4:5]
	s_waitcnt lgkmcnt(0)
	s_barrier

.LBB0_713:
	s_or_b64 exec, exec, s[10:11]
.LBB0_714:
	s_or_b64 exec, exec, s[4:5]
	s_waitcnt lgkmcnt(0)
	s_barrier

.LBB0_807:
	s_or_b64 exec, exec, s[10:11]
.LBB0_808:
	s_or_b64 exec, exec, s[4:5]
	s_waitcnt lgkmcnt(0)
	s_barrier

.LBB0_904:
	s_or_b64 exec, exec, s[10:11]
.LBB0_905:
	s_or_b64 exec, exec, s[4:5]
	s_waitcnt lgkmcnt(0)
	s_barrier

.LBB0_984:
	s_or_b64 exec, exec, s[10:11]
.LBB0_985:
	s_or_b64 exec, exec, s[4:5]
	s_waitcnt lgkmcnt(0)
	s_barrier

.LBB0_1078:
	s_or_b64 exec, exec, s[10:11]
.LBB0_1079:
	s_or_b64 exec, exec, s[4:5]
	s_waitcnt lgkmcnt(0)
	s_barrier

.LBB0_1175:
	s_or_b64 exec, exec, s[10:11]
.LBB0_1176:
	s_or_b64 exec, exec, s[4:5]
	s_waitcnt lgkmcnt(0)
	s_barrier

.LBB0_1247:
	s_or_b64 exec, exec, s[10:11]
.LBB0_1248:
	s_or_b64 exec, exec, s[4:5]
	s_waitcnt lgkmcnt(0)
	s_barrier

.LBB0_1324:
	s_or_b64 exec, exec, s[10:11]
.LBB0_1325:
	s_or_b64 exec, exec, s[4:5]
	s_waitcnt lgkmcnt(0)
	s_barrier

.LBB0_1410:
	s_or_b64 exec, exec, s[10:11]
.LBB0_1411:
	s_or_b64 exec, exec, s[4:5]
	s_waitcnt lgkmcnt(0)
	s_barrier

.LBB0_1491:
	s_or_b64 exec, exec, s[10:11]
.LBB0_1492:
	s_or_b64 exec, exec, s[4:5]
	s_waitcnt lgkmcnt(0)
	s_barrier

.LBB0_1571:
	s_or_b64 exec, exec, s[10:11]
.LBB0_1572:
	s_or_b64 exec, exec, s[4:5]
	s_waitcnt lgkmcnt(0)
	s_barrier

.LBB0_1665:
	s_or_b64 exec, exec, s[10:11]
.LBB0_1666:
	s_or_b64 exec, exec, s[4:5]
	s_waitcnt lgkmcnt(0)
	s_barrier

.LBB0_1762:
	s_or_b64 exec, exec, s[10:11]
.LBB0_1763:
	s_or_b64 exec, exec, s[4:5]
	s_waitcnt lgkmcnt(0)
	s_barrier

.LBB0_1842:
	s_or_b64 exec, exec, s[10:11]
.LBB0_1843:
	s_or_b64 exec, exec, s[4:5]
	s_waitcnt lgkmcnt(0)
	s_barrier

.LBB0_1936:
	s_or_b64 exec, exec, s[10:11]
.LBB0_1937:
	s_or_b64 exec, exec, s[4:5]
	s_waitcnt lgkmcnt(0)
	s_barrier

.LBB0_2033:
	s_or_b64 exec, exec, s[10:11]
.LBB0_2034:
	s_or_b64 exec, exec, s[4:5]
	s_waitcnt lgkmcnt(0)
	s_barrier

.LBB0_2105:
	s_or_b64 exec, exec, s[10:11]
.LBB0_2106:
	s_or_b64 exec, exec, s[4:5]
	s_waitcnt lgkmcnt(0)
	s_barrier

.LBB0_2285:
	s_or_b64 exec, exec, s[8:9]
.LBB0_2286:
	s_or_b64 exec, exec, s[0:1]
	v_readlane_b32 s42, v254, 56
	v_readlane_b32 s43, v254, 57
	s_mov_b32 s86, s54
	s_mov_b32 s87, s55
	s_waitcnt lgkmcnt(0)
	s_barrier

.LBB0_2366:
	s_or_b64 exec, exec, s[8:9]
.LBB0_2367:
	s_or_b64 exec, exec, s[0:1]
	s_waitcnt lgkmcnt(0)
	s_barrier

.LBB0_2446:
	s_or_b64 exec, exec, s[8:9]
.LBB0_2447:
	s_or_b64 exec, exec, s[0:1]
	s_waitcnt lgkmcnt(0)
	s_barrier

.LBB0_2540:
	s_or_b64 exec, exec, s[8:9]
.LBB0_2541:
	s_or_b64 exec, exec, s[0:1]
	s_waitcnt lgkmcnt(0)
	s_barrier

.LBB0_2637:
	s_or_b64 exec, exec, s[8:9]
.LBB0_2638:
	s_or_b64 exec, exec, s[0:1]
	s_waitcnt lgkmcnt(0)
	s_barrier

.LBB0_2717:
	s_or_b64 exec, exec, s[8:9]
.LBB0_2718:
	s_or_b64 exec, exec, s[0:1]
	s_waitcnt lgkmcnt(0)
	s_barrier

.LBB0_2811:
	s_or_b64 exec, exec, s[8:9]
.LBB0_2812:
	s_or_b64 exec, exec, s[0:1]
	s_waitcnt lgkmcnt(0)
	s_barrier

.LBB0_2908:
	s_or_b64 exec, exec, s[8:9]
.LBB0_2909:
	s_or_b64 exec, exec, s[0:1]
	s_waitcnt lgkmcnt(0)
	s_barrier

.LBB0_2980:
	s_or_b64 exec, exec, s[8:9]
.LBB0_2981:
	s_or_b64 exec, exec, s[0:1]
	s_waitcnt lgkmcnt(0)
	s_barrier

.LBB0_3078:
	s_or_b64 exec, exec, s[8:9]
.LBB0_3079:
	s_or_b64 exec, exec, s[0:1]
	s_waitcnt lgkmcnt(0)
	s_barrier

.LBB0_3141:
	s_or_b64 exec, exec, s[8:9]
.LBB0_3142:
	s_or_b64 exec, exec, s[0:1]
	s_waitcnt lgkmcnt(0)
	s_barrier

.LBB0_3202:
	s_or_b64 exec, exec, s[8:9]
.LBB0_3203:
	s_or_b64 exec, exec, s[0:1]
	s_waitcnt lgkmcnt(0)
	s_barrier

.LBB0_3283:
	s_or_b64 exec, exec, s[8:9]
.LBB0_3284:
	s_or_b64 exec, exec, s[0:1]
	s_waitcnt lgkmcnt(0)
	s_barrier

.LBB0_3363:
	s_or_b64 exec, exec, s[8:9]
.LBB0_3364:
	s_or_b64 exec, exec, s[0:1]
	s_waitcnt lgkmcnt(0)
	s_barrier

.LBB0_3457:
	s_or_b64 exec, exec, s[8:9]
.LBB0_3458:
	s_or_b64 exec, exec, s[0:1]
	s_waitcnt lgkmcnt(0)
	s_barrier

.LBB0_3555:
	s_or_b64 exec, exec, s[6:7]
.LBB0_3556:
	s_or_b64 exec, exec, s[0:1]
	s_waitcnt lgkmcnt(0)
	s_barrier

.LBB0_3625:
	s_or_b64 exec, exec, s[6:7]
.LBB0_3626:
	s_or_b64 exec, exec, s[0:1]
	s_waitcnt lgkmcnt(0)
	s_barrier
